# counted lgkmcnt waits (lever 1) in the attention QK chains on top of the 16-byte-access version
# baseline (speedup 1.0000x reference)
; #define LAS __attribute__((address_space(3)))
; #define WG_BAR() do { asm volatile("s_waitcnt lgkmcnt(0)" ::: "memory"); __builtin_amdgcn_s_barrier(); asm volatile("" ::: "memory"); } while (0)
; template <int MODE, class Dec>
; __device__ __forceinline__ void attn_phase(const Frame& F, const bf16* Q, const bf16* K, const bf16* V, int nunits, const Dec dec, const bf16* O3, const float* L2, const float* L3) {
;     ...
;         WG_BAR();
;         const float sl = exp2f(-0.5f * (float)(h + 1)) * LOG2E * (float)d, cb = -sl * (float)(128 + ql - 4 * g);
;         f32x4 s[9];
;         __builtin_amdgcn_s_setprio(1);
; #pragma unroll
;         for (int tt = 0; tt < 9; ++tt) {
;             s[tt] = (f32x4){fmaf(sl, (float)(16 * tt), cb), fmaf(sl, (float)(16 * tt + 1), cb), fmaf(sl, (float)(16 * tt + 2), cb), fmaf(sl, (float)(16 * tt + 3), cb)};
; #pragma unroll
;             for (int ks = 0; ks < 4; ++ks) { const bf16x8 a = *(const LAS bf16x8*)(kb + ksw[ks] + tt * 4096); s[tt] = __builtin_amdgcn_mfma_f32_16x16x32_bf16(a, qf[ks], s[tt], 0, 0, 0); }
;         }
;         __builtin_amdgcn_s_setprio(0);
;         WG_BAR();
.LBB0_448:
	s_add_i32 s34, s56, 1
	v_cvt_f32_u32_e32 v16, s34
	s_mov_b32 s34, 0xc2fc0000
	s_waitcnt lgkmcnt(0)
	s_barrier
	v_mul_f32_e32 v17, -0.5, v16
	v_cmp_gt_f32_e32 vcc, s34, v17
	s_and_b64 s[34:35], vcc, exec
	s_cselect_b32 s34, 0xffffffc0, 0
	v_cndmask_b32_e32 v17, 0, v100, vcc
	v_fmac_f32_e32 v17, -0.5, v16
	v_exp_f32_e32 v16, v17
	v_cvt_f32_u32_e32 v17, s82
	v_ldexp_f32 v16, v16, s34
	v_mul_f32_e32 v16, 0x3fb8aa3b, v16
	v_mul_f32_e32 v80, v16, v17
	v_mul_f32_e64 v82, v81, -v80
	s_setprio 1
	ds_read_b128 v[16:19], v96
	ds_read_b128 v[20:23], v96 offset:4096
	s_mov_b32 s34, 2.0
	s_mov_b32 s35, 0x40400000
	v_pk_fma_f32 v[26:27], v[80:81], s[34:35], v[82:83] op_sel_hi:[0,1,0]
	s_mov_b32 s34, 0x41900000
	v_fma_f32 v24, 0, v80, v82
	v_fma_f32 v25, v81, -v80, v80
	s_mov_b32 s35, 0x41980000
	ds_read_b128 v[48:51], v96 offset:32768
	ds_read_b128 v[28:31], v96 offset:8192
	s_waitcnt lgkmcnt(2)
	v_mfma_f32_16x16x32_bf16 v[16:19], v[16:19], v[12:15], v[24:27]
	s_nop 2
	v_fma_f32 v26, v80, s34, v82
	v_fma_f32 v27, v80, s35, v82
	s_mov_b32 s34, 0x41800000
	s_mov_b32 s35, 0x41880000
	v_pk_fma_f32 v[24:25], v[80:81], s[34:35], v[82:83] op_sel_hi:[0,1,0]
	s_mov_b32 s34, 0x42080000
	s_mov_b32 s35, 0x420c0000
	v_mfma_f32_16x16x32_bf16 v[20:23], v[20:23], v[12:15], v[24:27]
	s_nop 2
	ds_read_b128 v[24:27], v97
	ds_read_b128 v[32:35], v97 offset:4096
	s_waitcnt lgkmcnt(1)
	v_mfma_f32_16x16x32_bf16 v[16:19], v[24:27], v[8:11], v[16:19]
	ds_read_b128 v[24:27], v98
	ds_read_b128 v[104:107], v98 offset:32768
	s_waitcnt lgkmcnt(1)
	v_mfma_f32_16x16x32_bf16 v[16:19], v[24:27], v[4:7], v[16:19]
	ds_read_b128 v[24:27], v99
	ds_read_b128 v[36:39], v99 offset:4096
	s_waitcnt lgkmcnt(1)
	v_mfma_f32_16x16x32_bf16 v[44:47], v[24:27], v[0:3], v[16:19]
	v_mfma_f32_16x16x32_bf16 v[16:19], v[32:35], v[8:11], v[20:23]
	s_nop 2
	ds_read_b128 v[20:23], v98 offset:4096
	ds_read_b128 v[24:27], v98 offset:8192
	s_waitcnt lgkmcnt(1)
	v_mfma_f32_16x16x32_bf16 v[16:19], v[20:23], v[4:7], v[16:19]
	v_mfma_f32_16x16x32_bf16 v[36:39], v[36:39], v[0:3], v[16:19]
	s_nop 6
	v_fma_f32 v18, v80, s34, v82
	v_fma_f32 v19, v80, s35, v82
	s_mov_b32 s34, 0x42000000
	s_mov_b32 s35, 0x42040000
	v_pk_fma_f32 v[16:17], v[80:81], s[34:35], v[82:83] op_sel_hi:[0,1,0]
	s_mov_b32 s34, 0x42480000
	s_mov_b32 s35, 0x424c0000
	v_mfma_f32_16x16x32_bf16 v[16:19], v[28:31], v[12:15], v[16:19]
	ds_read_b128 v[20:23], v97 offset:8192
	ds_read_b128 v[28:31], v97 offset:12288
	s_waitcnt lgkmcnt(1)
	v_mfma_f32_16x16x32_bf16 v[16:19], v[20:23], v[8:11], v[16:19]
	ds_read_b128 v[20:23], v99 offset:8192
	v_mfma_f32_16x16x32_bf16 v[16:19], v[24:27], v[4:7], v[16:19]
	ds_read_b128 v[24:27], v96 offset:12288
	ds_read_b128 v[40:43], v99 offset:12288
	s_waitcnt lgkmcnt(1)
	v_mfma_f32_16x16x32_bf16 v[32:35], v[20:23], v[0:3], v[16:19]
	ds_read_b128 v[20:23], v96 offset:16384
	s_nop 2
	v_pk_fma_f32 v[18:19], v[80:81], s[34:35], v[82:83] op_sel_hi:[0,1,0]
	s_mov_b32 s34, 0x42400000
	s_mov_b32 s35, 0x42440000
	v_pk_fma_f32 v[16:17], v[80:81], s[34:35], v[82:83] op_sel_hi:[0,1,0]
	s_mov_b32 s34, 0x42840000
	s_mov_b32 s35, 0x42860000
	v_mfma_f32_16x16x32_bf16 v[16:19], v[24:27], v[12:15], v[16:19]
	ds_read_b128 v[24:27], v98 offset:12288
	ds_read_b128 v[108:111], v98 offset:16384
	v_mfma_f32_16x16x32_bf16 v[16:19], v[28:31], v[8:11], v[16:19]
	s_waitcnt lgkmcnt(1)
	v_mfma_f32_16x16x32_bf16 v[16:19], v[24:27], v[4:7], v[16:19]
	v_mfma_f32_16x16x32_bf16 v[28:31], v[40:43], v[0:3], v[16:19]
	s_nop 6
	v_fma_f32 v18, v80, s34, v82
	v_fma_f32 v19, v80, s35, v82
	s_mov_b32 s34, 0x42800000
	s_mov_b32 s35, 0x42820000
	v_pk_fma_f32 v[16:17], v[80:81], s[34:35], v[82:83] op_sel_hi:[0,1,0]
	s_mov_b32 s34, 0x42a40000
	s_mov_b32 s35, 0x42a60000
	v_mfma_f32_16x16x32_bf16 v[16:19], v[20:23], v[12:15], v[16:19]
	ds_read_b128 v[20:23], v97 offset:16384
	ds_read_b128 v[40:43], v97 offset:20480
	s_waitcnt lgkmcnt(1)
	v_mfma_f32_16x16x32_bf16 v[16:19], v[20:23], v[8:11], v[16:19]
	ds_read_b128 v[20:23], v99 offset:16384
	v_mfma_f32_16x16x32_bf16 v[16:19], v[108:111], v[4:7], v[16:19]
	ds_read_b128 v[108:111], v96 offset:20480
	ds_read_b128 v[112:115], v99 offset:20480
	ds_read_b128 v[116:119], v96 offset:24576
	s_waitcnt lgkmcnt(2)
	v_mfma_f32_16x16x32_bf16 v[24:27], v[20:23], v[0:3], v[16:19]
	s_nop 2
	v_fma_f32 v18, v80, s34, v82
	v_fma_f32 v19, v80, s35, v82
	s_mov_b32 s34, 0x42a00000
	s_mov_b32 s35, 0x42a20000
	v_pk_fma_f32 v[16:17], v[80:81], s[34:35], v[82:83] op_sel_hi:[0,1,0]
	s_mov_b32 s34, 0x42c40000
	s_mov_b32 s35, 0x42c60000
	v_mfma_f32_16x16x32_bf16 v[16:19], v[108:111], v[12:15], v[16:19]
	v_mfma_f32_16x16x32_bf16 v[16:19], v[40:43], v[8:11], v[16:19]
	ds_read_b128 v[20:23], v98 offset:20480
	ds_read_b128 v[40:43], v98 offset:24576
	s_waitcnt lgkmcnt(1)
	v_mfma_f32_16x16x32_bf16 v[16:19], v[20:23], v[4:7], v[16:19]
	v_mfma_f32_16x16x32_bf16 v[20:23], v[112:115], v[0:3], v[16:19]
	ds_read_b128 v[108:111], v97 offset:24576
	ds_read_b128 v[112:115], v97 offset:28672
	s_nop 4
	v_pk_fma_f32 v[18:19], v[80:81], s[34:35], v[82:83] op_sel_hi:[0,1,0]
	v_pk_fma_f32 v[16:17], v[80:81], s[54:55], v[82:83] op_sel_hi:[0,1,0]
	s_nop 1
	v_mfma_f32_16x16x32_bf16 v[16:19], v[116:119], v[12:15], v[16:19]
	s_waitcnt lgkmcnt(1)
	v_mfma_f32_16x16x32_bf16 v[16:19], v[108:111], v[8:11], v[16:19]
	ds_read_b128 v[108:111], v99 offset:24576
	v_mfma_f32_16x16x32_bf16 v[16:19], v[40:43], v[4:7], v[16:19]
	ds_read_b128 v[40:43], v96 offset:28672
	ds_read_b128 v[116:119], v99 offset:28672
	ds_read_b128 v[120:123], v97 offset:32768
	s_waitcnt lgkmcnt(2)
	v_mfma_f32_16x16x32_bf16 v[16:19], v[108:111], v[0:3], v[16:19]
	v_fma_f32 v110, v80, s38, v82
	v_fma_f32 v111, v80, s39, v82
	v_pk_fma_f32 v[108:109], v[80:81], s[40:41], v[82:83] op_sel_hi:[0,1,0]
	s_nop 1
	v_mfma_f32_16x16x32_bf16 v[40:43], v[40:43], v[12:15], v[108:111]
	v_mfma_f32_16x16x32_bf16 v[40:43], v[112:115], v[8:11], v[40:43]
	s_nop 1
	ds_read_b128 v[108:111], v98 offset:28672
	ds_read_b128 v[112:115], v99 offset:32768
	s_waitcnt lgkmcnt(0)
	v_mfma_f32_16x16x32_bf16 v[40:43], v[108:111], v[4:7], v[40:43]
	v_fma_f32 v110, v80, s42, v82
	v_fma_f32 v111, v80, s43, v82
	v_pk_fma_f32 v[108:109], v[80:81], s[50:51], v[82:83] op_sel_hi:[0,1,0]
	v_mfma_f32_16x16x32_bf16 v[40:43], v[116:119], v[0:3], v[40:43]
	s_nop 0
	v_mfma_f32_16x16x32_bf16 v[48:51], v[48:51], v[12:15], v[108:111]
	v_mfma_f32_16x16x32_bf16 v[48:51], v[120:123], v[8:11], v[48:51]
	v_mfma_f32_16x16x32_bf16 v[48:51], v[104:107], v[4:7], v[48:51]
	v_mfma_f32_16x16x32_bf16 v[48:51], v[112:115], v[0:3], v[48:51]
	s_setprio 0
	s_waitcnt lgkmcnt(0)
	s_barrier
	v_cndmask_b32_e64 v79, 0, 1, s[66:67]
	v_cmp_ne_u32_e64 s[34:35], 1, v79
	s_andn2_b64 vcc, exec, s[66:67]
	s_cbranch_vccnz .LBB0_455
	s_lshl_b32 s96, s83, 11
	s_cmp_gt_i32 s81, 0
	s_mov_b64 s[66:67], -1
	s_cbranch_scc1 .LBB0_451
	s_add_i32 s95, s96, s79
	s_lshl_b32 s60, s94, 7
	s_mov_b64 s[66:67], 0

; #define LAS __attribute__((address_space(3)))
; #define WG_BAR() do { asm volatile("s_waitcnt lgkmcnt(0)" ::: "memory"); __builtin_amdgcn_s_barrier(); asm volatile("" ::: "memory"); } while (0)
; template <int MODE, class Dec>
; __device__ __forceinline__ void attn_phase(const Frame& F, const bf16* Q, const bf16* K, const bf16* V, int nunits, const Dec dec, const bf16* O3, const float* L2, const float* L3) {
;     ...
;         const int un = u + F.G; const bool has_next = un < nunits; if (has_next) dec(un, nxt);
;         const int n = cur.n, h = cur.h, d = cur.d;
;         const int qi = 16 * w + ql;
;         const size_t qrow = (size_t)(cur.b * SEQ + (n * 128 + qi) * d + cur.r);
;         WG_BAR();
;         const float sl = exp2f(-0.5f * (float)(h + 1)) * LOG2E * (float)d, cb = -sl * (float)(128 + ql - 4 * g);
;         f32x4 s[9];
;         __builtin_amdgcn_s_setprio(1);
; #pragma unroll
;         for (int tt = 0; tt < 9; ++tt) {
;             s[tt] = (f32x4){fmaf(sl, (float)(16 * tt), cb), fmaf(sl, (float)(16 * tt + 1), cb), fmaf(sl, (float)(16 * tt + 2), cb), fmaf(sl, (float)(16 * tt + 3), cb)};
; #pragma unroll
;             for (int ks = 0; ks < 4; ++ks) { const bf16x8 a = *(const LAS bf16x8*)(kb + ksw[ks] + tt * 4096); s[tt] = __builtin_amdgcn_mfma_f32_16x16x32_bf16(a, qf[ks], s[tt], 0, 0, 0); }
;         }
.LBB0_539:
	s_cmpk_lt_i32 s62, 0x800
	s_cselect_b64 s[50:51], -1, 0
	s_cmpk_gt_i32 s62, 0x7ff
	s_mov_b32 s92, s34
	s_cselect_b64 s[2:3], -1, 0
	s_lshl_b32 s48, s48, 11
	s_lshl_b32 s66, s65, 7
	s_add_i32 s48, s48, s66
	s_add_i32 s66, s92, 1
	v_cvt_f32_u32_e32 v16, s66
	v_add_u32_e32 v52, s48, v130
	s_mov_b32 s48, 0xc2fc0000
	s_bfe_u32 s34, s62, 0x40004
	v_mul_f32_e32 v17, -0.5, v16
	v_cmp_gt_f32_e32 vcc, s48, v17
	s_ashr_i32 s64, s62, 8
	s_and_b64 s[66:67], vcc, exec
	v_cndmask_b32_e32 v17, 0, v144, vcc
	v_fmac_f32_e32 v17, -0.5, v16
	v_exp_f32_e32 v16, v17
	s_waitcnt lgkmcnt(0)
	s_barrier
	s_cselect_b32 s48, 0xffffffc0, 0
	v_ldexp_f32 v16, v16, s48
	v_mul_f32_e32 v54, 0x3fb8aa3b, v16
	v_mul_f32_e64 v56, v131, -v54
	s_setprio 1
	ds_read_b128 v[20:23], v140
	ds_read_b128 v[48:51], v140 offset:28672
	s_mov_b32 s66, 2.0
	s_mov_b32 s67, 0x40400000
	v_fma_f32 v16, 0, v54, v56
	v_fma_f32 v17, v131, -v54, v54
	v_pk_fma_f32 v[18:19], v[54:55], s[66:67], v[56:57] op_sel_hi:[0,1,0]
	s_mov_b32 s66, 0x41900000
	s_mov_b32 s67, 0x41980000
	s_waitcnt lgkmcnt(1)
	v_mfma_f32_16x16x32_bf16 v[16:19], v[20:23], v[0:3], v[16:19]
	ds_read_b128 v[20:23], v141
	v_ashrrev_i32_e32 v53, 31, v52
	s_waitcnt lgkmcnt(0)
	v_mfma_f32_16x16x32_bf16 v[16:19], v[20:23], v[4:7], v[16:19]
	ds_read_b128 v[20:23], v142
	s_waitcnt lgkmcnt(0)
	v_mfma_f32_16x16x32_bf16 v[16:19], v[20:23], v[8:11], v[16:19]
	ds_read_b128 v[20:23], v143
	s_waitcnt lgkmcnt(0)
	v_mfma_f32_16x16x32_bf16 v[44:47], v[20:23], v[12:15], v[16:19]
	ds_read_b128 v[20:23], v140 offset:4096
	s_nop 3
	v_pk_fma_f32 v[18:19], v[54:55], s[66:67], v[56:57] op_sel_hi:[0,1,0]
	s_mov_b32 s66, 0x41800000
	s_mov_b32 s67, 0x41880000
	v_pk_fma_f32 v[16:17], v[54:55], s[66:67], v[56:57] op_sel_hi:[0,1,0]
	s_mov_b32 s66, 0x42080000
	s_mov_b32 s67, 0x420c0000
	s_waitcnt lgkmcnt(0)
	v_mfma_f32_16x16x32_bf16 v[16:19], v[20:23], v[0:3], v[16:19]
	ds_read_b128 v[20:23], v141 offset:4096
	s_waitcnt lgkmcnt(0)
	v_mfma_f32_16x16x32_bf16 v[16:19], v[20:23], v[4:7], v[16:19]
	ds_read_b128 v[20:23], v142 offset:4096
	s_waitcnt lgkmcnt(0)
	v_mfma_f32_16x16x32_bf16 v[16:19], v[20:23], v[8:11], v[16:19]
	ds_read_b128 v[20:23], v143 offset:4096
	s_waitcnt lgkmcnt(0)
	v_mfma_f32_16x16x32_bf16 v[40:43], v[20:23], v[12:15], v[16:19]
	ds_read_b128 v[20:23], v140 offset:8192
	s_nop 3
	v_pk_fma_f32 v[18:19], v[54:55], s[66:67], v[56:57] op_sel_hi:[0,1,0]
	s_mov_b32 s66, 0x42000000
	s_mov_b32 s67, 0x42040000
	v_pk_fma_f32 v[16:17], v[54:55], s[66:67], v[56:57] op_sel_hi:[0,1,0]
	s_mov_b32 s66, 0x42480000
	s_mov_b32 s67, 0x424c0000
	s_waitcnt lgkmcnt(0)
	v_mfma_f32_16x16x32_bf16 v[16:19], v[20:23], v[0:3], v[16:19]
	ds_read_b128 v[20:23], v141 offset:8192
	s_waitcnt lgkmcnt(0)
	v_mfma_f32_16x16x32_bf16 v[16:19], v[20:23], v[4:7], v[16:19]
	ds_read_b128 v[20:23], v142 offset:8192
	s_waitcnt lgkmcnt(0)
	v_mfma_f32_16x16x32_bf16 v[16:19], v[20:23], v[8:11], v[16:19]
	ds_read_b128 v[20:23], v143 offset:8192
	s_waitcnt lgkmcnt(0)
	v_mfma_f32_16x16x32_bf16 v[36:39], v[20:23], v[12:15], v[16:19]
	ds_read_b128 v[20:23], v140 offset:12288
	s_nop 3
	v_pk_fma_f32 v[18:19], v[54:55], s[66:67], v[56:57] op_sel_hi:[0,1,0]
	s_mov_b32 s66, 0x42400000
	s_mov_b32 s67, 0x42440000
	v_pk_fma_f32 v[16:17], v[54:55], s[66:67], v[56:57] op_sel_hi:[0,1,0]
	s_mov_b32 s66, 0x42800000
	s_mov_b32 s67, 0x42820000
	s_waitcnt lgkmcnt(0)
	v_mfma_f32_16x16x32_bf16 v[16:19], v[20:23], v[0:3], v[16:19]
	ds_read_b128 v[20:23], v141 offset:12288
	s_waitcnt lgkmcnt(0)
	v_mfma_f32_16x16x32_bf16 v[16:19], v[20:23], v[4:7], v[16:19]
	ds_read_b128 v[20:23], v142 offset:12288
	s_waitcnt lgkmcnt(0)
	v_mfma_f32_16x16x32_bf16 v[16:19], v[20:23], v[8:11], v[16:19]
	ds_read_b128 v[20:23], v143 offset:12288
	s_waitcnt lgkmcnt(0)
	v_mfma_f32_16x16x32_bf16 v[32:35], v[20:23], v[12:15], v[16:19]
	ds_read_b128 v[20:23], v140 offset:16384
	s_nop 3
	v_pk_fma_f32 v[18:19], v[54:55], s[70:71], v[56:57] op_sel_hi:[0,1,0]
	v_pk_fma_f32 v[16:17], v[54:55], s[66:67], v[56:57] op_sel_hi:[0,1,0]
	s_and_b32 s66, s62, 15
	s_waitcnt lgkmcnt(0)
	v_mfma_f32_16x16x32_bf16 v[16:19], v[20:23], v[0:3], v[16:19]
	ds_read_b128 v[20:23], v141 offset:16384
	s_waitcnt lgkmcnt(0)
	v_mfma_f32_16x16x32_bf16 v[16:19], v[20:23], v[4:7], v[16:19]
	ds_read_b128 v[20:23], v142 offset:16384
	s_waitcnt lgkmcnt(0)
	v_mfma_f32_16x16x32_bf16 v[16:19], v[20:23], v[8:11], v[16:19]
	ds_read_b128 v[20:23], v143 offset:16384
	s_waitcnt lgkmcnt(0)
	v_mfma_f32_16x16x32_bf16 v[28:31], v[20:23], v[12:15], v[16:19]
	ds_read_b128 v[20:23], v140 offset:20480
	s_nop 3
	v_pk_fma_f32 v[18:19], v[54:55], s[72:73], v[56:57] op_sel_hi:[0,1,0]
	v_pk_fma_f32 v[16:17], v[54:55], s[74:75], v[56:57] op_sel_hi:[0,1,0]
	s_waitcnt lgkmcnt(0)
	s_nop 0
	v_mfma_f32_16x16x32_bf16 v[16:19], v[20:23], v[0:3], v[16:19]
	ds_read_b128 v[20:23], v141 offset:20480
	s_waitcnt lgkmcnt(0)
; #define LAS __attribute__((address_space(3)))
; #define WG_BAR() do { asm volatile("s_waitcnt lgkmcnt(0)" ::: "memory"); __builtin_amdgcn_s_barrier(); asm volatile("" ::: "memory"); } while (0)
; template <int MODE, class Dec>
; __device__ __forceinline__ void attn_phase(const Frame& F, const bf16* Q, const bf16* K, const bf16* V, int nunits, const Dec dec, const bf16* O3, const float* L2, const float* L3) {
;     ...
;         for (int tt = 0; tt < 9; ++tt) {
;             s[tt] = (f32x4){fmaf(sl, (float)(16 * tt), cb), fmaf(sl, (float)(16 * tt + 1), cb), fmaf(sl, (float)(16 * tt + 2), cb), fmaf(sl, (float)(16 * tt + 3), cb)};
; #pragma unroll
;             for (int ks = 0; ks < 4; ++ks) { const bf16x8 a = *(const LAS bf16x8*)(kb + ksw[ks] + tt * 4096); s[tt] = __builtin_amdgcn_mfma_f32_16x16x32_bf16(a, qf[ks], s[tt], 0, 0, 0); }
;         }
;         __builtin_amdgcn_s_setprio(0);
;         WG_BAR();
;         v2u a2[8], a3[8]; float l2v = 0.f, l3v = 0.f;
;         bf16* op = cur.Og + qrow * (size_t)cur.ldo + h * 128 + 4 * g;
;         if (MODE == 1) { const bf16* o3p = O3 + qrow * 2048 + h * 128 + 4 * g;
; #pragma unroll
;             for (int dt = 0; dt < 8; ++dt) { a2[dt] = *(const v2u*)(op + 16 * dt); a3[dt] = *(const v2u*)(o3p + 16 * dt); }
;             l2v = L2[qrow * 16 + h]; l3v = L3[qrow * 16 + h]; }
;         if (has_next) { attn_issue<false>(F, K, nxt, 0);
;             q_load4(Q + (size_t)(nxt.b * SEQ + (nxt.n * 128 + qi) * nxt.d + nxt.r) * 2048 + nxt.h * 128 + 8 * g, qn); }
	v_mfma_f32_16x16x32_bf16 v[16:19], v[20:23], v[4:7], v[16:19]
	ds_read_b128 v[20:23], v142 offset:20480
	s_waitcnt lgkmcnt(0)
	v_mfma_f32_16x16x32_bf16 v[16:19], v[20:23], v[8:11], v[16:19]
	ds_read_b128 v[20:23], v143 offset:20480
	s_waitcnt lgkmcnt(0)
	v_mfma_f32_16x16x32_bf16 v[24:27], v[20:23], v[12:15], v[16:19]
	ds_read_b128 v[20:23], v140 offset:24576
	s_nop 3
	v_pk_fma_f32 v[18:19], v[54:55], s[76:77], v[56:57] op_sel_hi:[0,1,0]
	v_pk_fma_f32 v[16:17], v[54:55], s[80:81], v[56:57] op_sel_hi:[0,1,0]
	s_waitcnt lgkmcnt(0)
	s_nop 0
	v_mfma_f32_16x16x32_bf16 v[16:19], v[20:23], v[0:3], v[16:19]
	ds_read_b128 v[20:23], v141 offset:24576
	s_waitcnt lgkmcnt(0)
	v_mfma_f32_16x16x32_bf16 v[16:19], v[20:23], v[4:7], v[16:19]
	ds_read_b128 v[20:23], v142 offset:24576
	s_waitcnt lgkmcnt(0)
	v_mfma_f32_16x16x32_bf16 v[16:19], v[20:23], v[8:11], v[16:19]
	ds_read_b128 v[20:23], v143 offset:24576
	s_waitcnt lgkmcnt(0)
	v_mfma_f32_16x16x32_bf16 v[20:23], v[20:23], v[12:15], v[16:19]
	s_nop 4
	v_fma_f32 v18, v54, s96, v56
	v_fma_f32 v19, v54, s97, v56
	v_pk_fma_f32 v[16:17], v[54:55], s[94:95], v[56:57] op_sel_hi:[0,1,0]
	s_nop 1
	v_mfma_f32_16x16x32_bf16 v[16:19], v[48:51], v[0:3], v[16:19]
	ds_read_b128 v[48:51], v141 offset:28672
	s_waitcnt lgkmcnt(0)
	v_mfma_f32_16x16x32_bf16 v[16:19], v[48:51], v[4:7], v[16:19]
	ds_read_b128 v[48:51], v142 offset:28672
	s_waitcnt lgkmcnt(0)
	v_mfma_f32_16x16x32_bf16 v[16:19], v[48:51], v[8:11], v[16:19]
	ds_read_b128 v[48:51], v143 offset:28672
	s_waitcnt lgkmcnt(0)
	v_mfma_f32_16x16x32_bf16 v[16:19], v[48:51], v[12:15], v[16:19]
	v_fma_f32 v50, v54, s78, v56
	v_fma_f32 v51, v54, s79, v56
	v_pk_fma_f32 v[48:49], v[54:55], s[82:83], v[56:57] op_sel_hi:[0,1,0]
	ds_read_b128 v[54:57], v140 offset:32768
	s_waitcnt lgkmcnt(0)
	v_mfma_f32_16x16x32_bf16 v[48:51], v[54:57], v[0:3], v[48:51]
	ds_read_b128 v[54:57], v141 offset:32768
	s_waitcnt lgkmcnt(0)
	v_mfma_f32_16x16x32_bf16 v[48:51], v[54:57], v[4:7], v[48:51]
	ds_read_b128 v[54:57], v142 offset:32768
	s_waitcnt lgkmcnt(0)
	v_mfma_f32_16x16x32_bf16 v[48:51], v[54:57], v[8:11], v[48:51]
	ds_read_b128 v[54:57], v143 offset:32768
	s_waitcnt lgkmcnt(0)
	v_mfma_f32_16x16x32_bf16 v[48:51], v[54:57], v[12:15], v[48:51]
	s_setprio 0
	v_lshlrev_b64 v[54:55], 13, v[52:53]
	v_lshl_add_u64 v[54:55], s[86:87], 0, v[54:55]
	s_lshl_b32 s48, s92, 8
	v_lshl_add_u64 v[54:55], v[54:55], 0, s[48:49]
	v_lshl_add_u64 v[92:93], v[54:55], 0, v[74:75]
	v_lshlrev_b64 v[54:55], 12, v[52:53]
	v_lshl_add_u64 v[54:55], s[42:43], 0, v[54:55]
	s_waitcnt lgkmcnt(0)
	s_barrier
	v_lshl_add_u64 v[54:55], v[54:55], 0, s[48:49]
	v_lshl_add_u64 v[54:55], v[54:55], 0, v[74:75]
	v_bfe_u32 v242, v156, 4, 1
	v_mul_u32_u24_e32 v242, 24, v242
	v_mov_b32_e32 v243, 0
	v_lshl_add_u64 v[240:241], v[92:93], 0, v[242:243]
	v_lshl_add_u64 v[244:245], v[54:55], 0, v[242:243]
	global_load_dwordx4 v[94:97], v[240:241], off
	global_load_dwordx4 v[98:101], v[244:245], off
	global_load_dwordx4 v[102:105], v[240:241], off offset:64
	global_load_dwordx4 v[106:109], v[244:245], off offset:64
	global_load_dwordx4 v[110:113], v[240:241], off offset:128
	global_load_dwordx4 v[114:117], v[244:245], off offset:128
	global_load_dwordx4 v[118:121], v[240:241], off offset:192
	global_load_dwordx4 v[122:125], v[244:245], off offset:192
	s_mov_b32 s93, s49
	v_lshlrev_b64 v[52:53], 6, v[52:53]
	s_lshl_b64 s[68:69], s[92:93], 2
	v_or_b32_e32 v53, s69, v53
	v_or_b32_e32 v52, s68, v52
	v_lshl_add_u64 v[54:55], s[44:45], 0, v[52:53]
	v_lshl_add_u64 v[52:53], s[46:47], 0, v[52:53]
	global_load_dword v147, v[54:55], off
	global_load_dword v148, v[52:53], off
	s_and_b64 vcc, exec, s[2:3]
	s_cbranch_vccnz .LBB0_544
	s_lshl_b32 s67, s64, 11
	s_cmp_lg_u32 s66, 0
	s_cbranch_scc0 .LBB0_555
	s_lshl_b32 s68, s66, 7
	s_add_i32 s48, s68, s67
	s_add_i32 s69, s48, 0xffffff80
	v_add_u32_e32 v0, s69, v127
	v_ashrrev_i32_e32 v1, 31, v0
	v_lshlrev_b64 v[0:1], 11, v[0:1]
	s_lshl_b32 s48, s34, 7
	v_or_b32_e32 v0, v0, v82
	v_or_b32_e32 v0, s48, v0
	v_lshl_add_u64 v[0:1], v[0:1], 1, s[36:37]
	s_add_i32 m0, s35, 0
	s_nop 0
	global_load_lds_dwordx4 v[0:1], off
	v_add_u32_e32 v0, s69, v126
	v_ashrrev_i32_e32 v1, 31, v0
	v_lshlrev_b64 v[0:1], 11, v[0:1]
	v_or_b32_e32 v0, v0, v84
	v_or_b32_e32 v0, s48, v0
	v_lshl_add_u64 v[0:1], v[0:1], 1, s[36:37]
	s_add_i32 m0, s54, 0
	s_nop 0
	global_load_lds_dwordx4 v[0:1], off
	v_add_u32_e32 v0, s69, v128
	v_ashrrev_i32_e32 v1, 31, v0
	v_lshlrev_b64 v[0:1], 11, v[0:1]
	v_or_b32_e32 v0, v0, v86
	v_or_b32_e32 v0, s48, v0
	v_lshl_add_u64 v[0:1], v[0:1], 1, s[36:37]
	s_add_i32 m0, s55, 0
	s_nop 0
	global_load_lds_dwordx4 v[0:1], off
	v_add_u32_e32 v0, s69, v129
	v_ashrrev_i32_e32 v1, 31, v0
	v_lshlrev_b64 v[0:1], 11, v[0:1]
	v_or_b32_e32 v0, v0, v88
	v_or_b32_e32 v0, s48, v0
	v_lshl_add_u64 v[0:1], v[0:1], 1, s[36:37]
	s_add_i32 m0, s56, 0
	s_nop 0
	global_load_lds_dwordx4 v[0:1], off
	s_cbranch_execnz .LBB0_543
